# layer-0 weight conversion moved into phase 0 (before the first grid barrier); layer-0 norm1 rows panel-wise; its norm1|in-proj seam is a team barrier too
# speedup vs baseline: 1.0099x; 1.0078x over previous
.LBB0_388:
	s_andn2_b64 vcc, exec, s[2:3]
	s_cbranch_vccnz .LBB0_411
	s_waitcnt vmcnt(0)
	v_mov_b32_e32 v0, v200
	s_load_dword s14, s[38:39], 0x0
	v_ashrrev_i32_e32 v2, 6, v0
	v_add_u32_e32 v34, s61, v2
	v_sub_u32_e32 v2, 0, v34
	v_max_i32_e32 v2, v34, v2
	s_waitcnt lgkmcnt(0)
	s_bfe_i32 s15, s14, 0x1d0000
	s_abs_i32 s2, s15
	v_cvt_f32_u32_e32 v1, s2
	v_xor_b32_e32 v3, s15, v34
	s_sub_i32 s3, 0, s2
	v_ashrrev_i32_e32 v33, 31, v3
	v_rcp_iflag_f32_e32 v1, v1
	s_nop 0
	v_mul_f32_e32 v1, 0x4f7ffffe, v1
	v_cvt_u32_f32_e32 v1, v1
	v_mul_lo_u32 v3, s3, v1
	v_mul_hi_u32 v3, v1, v3
	v_add_u32_e32 v1, v1, v3
	v_mul_hi_u32 v1, v2, v1
	v_mul_lo_u32 v3, v1, s2
	v_sub_u32_e32 v2, v2, v3
	v_add_u32_e32 v4, 1, v1
	v_cmp_le_u32_e32 vcc, s2, v2
	v_subrev_u32_e32 v3, s2, v2
	s_nop 0
	v_cndmask_b32_e32 v1, v1, v4, vcc
	v_cndmask_b32_e32 v2, v2, v3, vcc
	v_add_u32_e32 v3, 1, v1
	v_cmp_le_u32_e32 vcc, s2, v2
	s_nop 1
	v_cndmask_b32_e32 v1, v1, v3, vcc
	v_xor_b32_e32 v35, v1, v33
	v_sub_u32_e32 v16, v35, v33
	s_bfe_u32 s100, s61, 0x30003
	v_mov_b32_e32 v16, s100
	v_cmp_gt_i32_e32 vcc, 8, v16
	s_and_saveexec_b64 s[2:3], vcc
	s_mov_b32 s16, 0x800000
	s_cbranch_execz .LBB0_393
	v_lshlrev_b32_e32 v1, 12, v16
	v_mul_lo_u32 v2, v16, s15
	v_add_u32_e32 v3, v1, v34
	v_sub_u32_e32 v32, v3, v2
	v_add_u32_e32 v52, 0x1000, v1
	s_lshr_b32 s101, s61, 6
	s_and_b32 s100, s101, 7
	s_lshr_b32 s101, s101, 3
	s_lshl_b32 s100, s100, 8
	s_lshl_b32 s101, s101, 3
	s_add_i32 s101, s101, s100
	s_bfe_u32 s100, s61, 0x30003
	s_lshl_b32 s100, s100, 12
	s_add_i32 s101, s101, s100
	s_mov_b32 s100, 0
	v_lshrrev_b32_e32 v32, 6, v200
	v_add_u32_e32 v32, s101, v32
	v_and_b32_e32 v52, 0xffffff00, v32
	v_add_u32_e32 v52, 0x100, v52
	v_cmp_lt_i32_e32 vcc, v32, v52
	s_and_b64 exec, exec, vcc
	s_cbranch_execz .LBB0_393
	v_and_b32_e32 v59, 63, v0
	v_readlane_b32 s40, v254, 61
	v_mov_b64_e32 v[18:19], s[0:1]
	v_lshlrev_b32_e32 v128, 4, v59
	v_readlane_b32 s48, v255, 5
	v_readlane_b32 s49, v255, 6
	v_mad_i64_i32 v[18:19], s[0:1], v16, s84, v[18:19]
	s_nop 3
	global_load_dwordx4 v[0:3], v128, s[48:49]
	global_load_dwordx4 v[4:7], v128, s[48:49] offset:1024
	global_load_dwordx4 v[8:11], v128, s[48:49] offset:2048
	global_load_dwordx4 v[12:15], v128, s[48:49] offset:3072
	v_lshl_add_u64 v[18:19], v[18:19], 0, v[128:129]
	v_readlane_b32 s0, v255, 25
	v_readlane_b32 s1, v255, 26
	global_load_dwordx4 v[38:41], v[18:19], off
	global_load_dwordx4 v[42:45], v[18:19], off offset:1024
	v_mov_b64_e32 v[20:21], s[0:1]
	v_mad_i64_i32 v[16:17], s[0:1], v16, s84, v[20:21]
	v_lshl_add_u64 v[28:29], v[16:17], 0, v[128:129]
	global_load_dwordx4 v[46:49], v[18:19], off offset:2048
	global_load_dwordx4 v[60:63], v[18:19], off offset:3072
	s_nop 0
	global_load_dwordx4 v[16:19], v[28:29], off
	global_load_dwordx4 v[20:23], v[28:29], off offset:1024
	global_load_dwordx4 v[24:27], v[28:29], off offset:2048
	s_nop 0
	global_load_dwordx4 v[28:31], v[28:29], off offset:3072
	v_cmp_lt_i32_e32 vcc, v206, v205
	v_xor_b32_e32 v51, 8, v204
	v_sub_u32_e32 v64, v33, v35
	v_cndmask_b32_e32 v36, v204, v206, vcc
	v_cmp_lt_i32_e32 vcc, v207, v205
	v_lshlrev_b32_e32 v65, 12, v33
	v_ashrrev_i32_e32 v33, 31, v32
	v_cndmask_b32_e32 v37, v204, v207, vcc
	v_cmp_lt_i32_e32 vcc, v252, v205
	v_lshlrev_b32_e32 v35, 12, v35
	v_lshlrev_b32_e32 v53, 2, v36
	v_cndmask_b32_e32 v50, v204, v252, vcc
	v_cmp_lt_i32_e32 vcc, v51, v205
	v_lshlrev_b32_e32 v54, 2, v37
	v_lshlrev_b32_e32 v55, 2, v50
	v_cndmask_b32_e32 v51, v204, v51, vcc
	v_cmp_lt_i32_e32 vcc, v210, v205
	v_lshlrev_b32_e32 v56, 2, v51
	v_mul_lo_u32 v64, v64, s15
	v_cndmask_b32_e32 v57, v204, v210, vcc
	v_cmp_lt_i32_e32 vcc, v211, v205
	v_lshlrev_b64 v[36:37], 11, v[32:33]
	v_lshlrev_b64 v[50:51], 12, v[32:33]
	v_readlane_b32 s12, v255, 13
	v_cndmask_b32_e32 v58, v204, v211, vcc
	s_mov_b32 s7, 0
	s_mov_b32 s6, 32
	v_add3_u32 v32, v34, v64, v35
	v_lshl_or_b32 v36, v59, 3, v36
	v_or_b32_e32 v50, v50, v128
	v_readlane_b32 s13, v255, 14
	v_lshlrev_b32_e32 v57, 2, v57
	v_lshlrev_b32_e32 v58, 2, v58
	s_lshl_b64 s[0:1], s[6:7], 11
	s_lshl_b64 s[6:7], s[6:7], 12
	v_sub_u32_e32 v59, v32, v65
	v_lshrrev_b32_e32 v59, 6, v200
	v_add_u32_e32 v59, s101, v59
	v_lshl_add_u64 v[32:33], s[8:9], 0, v[36:37]
	v_lshl_add_u64 v[34:35], s[12:13], 0, v[50:51]
	s_mov_b64 s[12:13], 0
	v_readlane_b32 s41, v254, 62
	v_readlane_b32 s42, v254, 63
	v_readlane_b32 s43, v255, 0
	v_readlane_b32 s44, v255, 1
	v_readlane_b32 s45, v255, 2
	v_readlane_b32 s46, v255, 3
	v_readlane_b32 s47, v255, 4
	v_readlane_b32 s50, v255, 7
	v_readlane_b32 s51, v255, 8
	v_readlane_b32 s52, v255, 9
	v_readlane_b32 s53, v255, 10
	v_readlane_b32 s54, v255, 11
	v_readlane_b32 s55, v255, 12
	s_waitcnt vmcnt(7)
	v_pk_add_f32 v[36:37], v[40:41], 1.0 op_sel_hi:[1,0]
	v_pk_add_f32 v[38:39], v[38:39], 1.0 op_sel_hi:[1,0]
	s_waitcnt vmcnt(6)
	v_pk_add_f32 v[40:41], v[44:45], 1.0 op_sel_hi:[1,0]
	v_pk_add_f32 v[42:43], v[42:43], 1.0 op_sel_hi:[1,0]
	s_waitcnt vmcnt(5)
	v_pk_add_f32 v[44:45], v[48:49], 1.0 op_sel_hi:[1,0]
	v_pk_add_f32 v[46:47], v[46:47], 1.0 op_sel_hi:[1,0]
	s_waitcnt vmcnt(4)
	v_pk_add_f32 v[48:49], v[62:63], 1.0 op_sel_hi:[1,0]
	v_pk_add_f32 v[50:51], v[60:61], 1.0 op_sel_hi:[1,0]
.LBB0_392:
	global_load_dwordx4 v[60:63], v[34:35], off offset:-3072 nt
	global_load_dwordx4 v[64:67], v[34:35], off offset:-2048 nt
	global_load_dwordx4 v[68:71], v[34:35], off offset:-1024 nt
	global_load_dwordx4 v[72:75], v[34:35], off nt
	v_add_u32_e32 v59, 32, v59
	v_cmp_ge_i32_e32 vcc, v59, v52
	s_or_b64 s[12:13], vcc, s[12:13]
	v_lshl_add_u64 v[34:35], v[34:35], 0, s[6:7]
	s_waitcnt vmcnt(3)
	v_pk_mul_f32 v[76:77], v[62:63], v[62:63]
	v_pk_mul_f32 v[78:79], v[60:61], v[60:61]
	s_waitcnt vmcnt(2)
	v_pk_mul_f32 v[80:81], v[66:67], v[66:67]
	v_pk_mul_f32 v[82:83], v[64:65], v[64:65]
	v_pk_mov_b32 v[88:89], v[78:79], v[76:77] op_sel:[1,0]
	v_mov_b32_e32 v79, v77
	v_pk_mov_b32 v[76:77], v[82:83], v[80:81] op_sel:[1,0]
	v_mov_b32_e32 v83, v81
	s_waitcnt vmcnt(0)
	v_mul_f32_e32 v87, v72, v72
	v_mul_f32_e32 v84, v69, v69
	v_mul_f32_e32 v86, v71, v71
	v_pk_add_f32 v[78:79], v[88:89], v[78:79]
	v_pk_add_f32 v[76:77], v[76:77], v[82:83]
	v_mul_f32_e32 v90, v73, v73
	v_mul_f32_e32 v91, v74, v74
	v_mul_f32_e32 v92, v75, v75
	v_pk_fma_f32 v[80:81], v[68:69], v[68:69], v[84:85] op_sel_hi:[1,1,0]
	v_pk_fma_f32 v[84:85], v[70:71], v[70:71], v[86:87] op_sel_hi:[1,1,0]
	v_pk_add_f32 v[78:79], v[78:79], v[78:79] op_sel:[0,1] op_sel_hi:[1,0]
	v_pk_add_f32 v[76:77], v[76:77], v[76:77] op_sel:[0,1] op_sel_hi:[1,0]
	v_mov_b32_e32 v81, v91
	v_mov_b32_e32 v85, v92
	v_mov_b32_e32 v79, v87
	v_mov_b32_e32 v77, v90
	v_pk_add_f32 v[80:81], v[80:81], v[84:85]
	v_pk_add_f32 v[76:77], v[78:79], v[76:77]
	s_nop 0
	v_pk_add_f32 v[76:77], v[76:77], v[80:81]
	s_nop 0
	v_add_f32_e32 v76, v76, v77
	ds_bpermute_b32 v77, v53, v76
	s_waitcnt lgkmcnt(0)
	v_add_f32_e32 v76, v76, v77
	ds_bpermute_b32 v77, v54, v76
	s_waitcnt lgkmcnt(0)
	v_add_f32_e32 v76, v76, v77
	ds_bpermute_b32 v77, v55, v76
	s_waitcnt lgkmcnt(0)
	v_add_f32_e32 v76, v76, v77
	ds_bpermute_b32 v77, v56, v76
	s_waitcnt lgkmcnt(0)
	v_add_f32_e32 v76, v76, v77
	ds_bpermute_b32 v77, v57, v76
	s_waitcnt lgkmcnt(0)
	v_add_f32_e32 v76, v76, v77
	ds_bpermute_b32 v77, v58, v76
	s_waitcnt lgkmcnt(0)
	v_add_f32_e32 v76, v76, v77
	v_fmamk_f32 v76, v76, 0x3a800000, v201
	v_mul_f32_e32 v77, 0x4b800000, v76
	v_cmp_gt_f32_e32 vcc, s16, v76
	s_nop 1
	v_cndmask_b32_e32 v76, v76, v77, vcc
	v_rsq_f32_e32 v76, v76
	s_nop 0
	v_mul_f32_e32 v77, 0x45800000, v76
	v_cndmask_b32_e32 v76, v76, v77, vcc
	v_pk_mul_f32 v[62:63], v[62:63], v[76:77] op_sel_hi:[1,0]
	v_pk_mul_f32 v[60:61], v[60:61], v[76:77] op_sel_hi:[1,0]
	v_pk_mul_f32 v[66:67], v[66:67], v[76:77] op_sel_hi:[1,0]
	v_pk_mul_f32 v[64:65], v[64:65], v[76:77] op_sel_hi:[1,0]
	v_pk_mul_f32 v[70:71], v[70:71], v[76:77] op_sel_hi:[1,0]
	v_pk_mul_f32 v[68:69], v[68:69], v[76:77] op_sel_hi:[1,0]
	v_pk_mul_f32 v[74:75], v[74:75], v[76:77] op_sel_hi:[1,0]
	v_pk_mul_f32 v[72:73], v[72:73], v[76:77] op_sel_hi:[1,0]
	v_pk_mul_f32 v[60:61], v[0:1], v[60:61]
	v_pk_mul_f32 v[62:63], v[2:3], v[62:63]
	v_pk_mul_f32 v[64:65], v[4:5], v[64:65]
	v_pk_mul_f32 v[66:67], v[6:7], v[66:67]
	v_pk_mul_f32 v[68:69], v[8:9], v[68:69]
	v_pk_mul_f32 v[70:71], v[10:11], v[70:71]
	v_pk_mul_f32 v[72:73], v[12:13], v[72:73]
	v_pk_mul_f32 v[74:75], v[14:15], v[74:75]
	v_pk_fma_f32 v[62:63], v[36:37], v[62:63], v[18:19]
	v_pk_fma_f32 v[60:61], v[38:39], v[60:61], v[16:17]
	v_pk_fma_f32 v[66:67], v[40:41], v[66:67], v[22:23]
	v_pk_fma_f32 v[64:65], v[42:43], v[64:65], v[20:21]
	v_pk_fma_f32 v[70:71], v[44:45], v[70:71], v[26:27]
	v_pk_fma_f32 v[68:69], v[46:47], v[68:69], v[24:25]
	v_pk_fma_f32 v[74:75], v[48:49], v[74:75], v[30:31]
	v_pk_fma_f32 v[72:73], v[50:51], v[72:73], v[28:29]
	v_cvt_pk_bf16_f32 v60, v60, v61
	v_cvt_pk_bf16_f32 v61, v62, v63
	v_cvt_pk_bf16_f32 v62, v64, v65
	v_cvt_pk_bf16_f32 v63, v66, v67
	v_cvt_pk_bf16_f32 v64, v68, v69
	v_cvt_pk_bf16_f32 v65, v70, v71
	v_cvt_pk_bf16_f32 v66, v72, v73
	v_cvt_pk_bf16_f32 v67, v74, v75
	global_store_dwordx2 v[32:33], v[60:61], off
	global_store_dwordx2 v[32:33], v[62:63], off offset:512
	global_store_dwordx2 v[32:33], v[64:65], off offset:1024
	global_store_dwordx2 v[32:33], v[66:67], off offset:1536
	v_lshl_add_u64 v[32:33], v[32:33], 0, s[0:1]
	s_andn2_b64 exec, exec, s[12:13]
	s_cbranch_execnz .LBB0_392
	s_or_b64 exec, exec, s[12:13]
	s_cmp_lg_u32 s100, 0
	s_cbranch_scc1 .Lnt_done_n0
	s_mov_b32 s100, 1
	s_mov_b64 s[12:13], 0
	v_add_u32_e32 v59, 0x700, v59
	v_add_u32_e32 v52, 0x800, v52
	s_mov_b32 vcc_lo, 0x380000
	s_mov_b32 vcc_hi, 0
	v_lshl_add_u64 v[32:33], v[32:33], 0, vcc
	s_mov_b32 vcc_lo, 0x700000
	v_lshl_add_u64 v[34:35], v[34:35], 0, vcc
	s_branch .LBB0_392
.Lnt_done_n0:
.LBB0_393:
	s_or_b64 exec, exec, s[2:3]
	s_cmp_eq_u32 s80, 1
	s_cbranch_scc1 .LBB0_411
.Lw0_entry:
	v_mov_b32_e32 v0, v200
	s_nop 0
	v_readfirstlane_b32 s0, v0
	s_ashr_i32 s0, s0, 6
	s_add_i32 s12, s0, s61
	s_cmpk_gt_i32 s12, 0xd3f
	s_cbranch_scc1 .LBB0_411
	s_mulk_i32 s0, 0x4100
	v_bfe_u32 v3, v0, 4, 2
	v_and_b32_e32 v2, 15, v0
	s_add_i32 s0, s0, 16
	v_and_b32_e32 v4, 7, v0
	v_bfe_u32 v1, v0, 3, 3
	v_lshlrev_b32_e32 v0, 2, v2
	v_lshlrev_b32_e32 v2, 4, v2
	v_mul_u32_u24_e32 v5, 0x104, v3
	s_lshl_b32 s13, s14, 3
	v_add3_u32 v6, s0, v2, v5
	v_lshlrev_b32_e32 v2, 3, v4
	v_mul_u32_u24_e32 v4, 0x820, v4
	v_lshlrev_b32_e32 v5, 2, v1
	v_add3_u32 v7, s0, v4, v5
	v_or_b32_e32 v8, 8, v1
	v_or_b32_e32 v9, 16, v1
	v_or_b32_e32 v10, 24, v1
	v_or_b32_e32 v11, 32, v1
	v_or_b32_e32 v12, 40, v1
	v_or_b32_e32 v13, 48, v1
	v_or_b32_e32 v14, 56, v1
	s_lshl_b32 s14, s12, 2
	s_lshl_b32 s15, s13, 2
	s_lshl_b32 s16, s12, 6
	s_lshl_b32 s17, s13, 6
	s_branch .LBB0_396

.LBB0_422:
	s_or_b64 exec, exec, s[2:3]
	v_readlane_b32 s38, v255, 18
	v_readlane_b32 s39, v255, 19
	s_waitcnt vmcnt(0) lgkmcnt(0)
	s_barrier
	s_load_dword s14, s[38:39], 0x0
	s_waitcnt lgkmcnt(0)
	s_branch .Lw0_entry
	s_add_i32 s80, s80, 1
	s_cmp_ge_i32 s80, s81
	s_mov_b64 s[0:1], -1
	s_cbranch_scc1 .LBB0_10

.Ltb_noreg:
	s_mov_b32 s2, 0xf0f84
	s_bitcmp1_b32 s2, s80
	s_cbranch_scc0 .Ltb_grid
	s_bfm_b32 s3, s80, 0
	s_and_b32 s3, s3, s2
	s_bcnt1_i32_b32 s3, s3
	s_add_i32 s3, s3, 1
	s_lshl_b32 s19, s3, 2
	v_readlane_b32 s6, v254, 44
	v_readlane_b32 s7, v254, 45
	s_bfe_u32 s13, s61, 0x60003
	s_and_b32 s14, s13, 7
	s_lshr_b32 s13, s13, 3
	s_lshl_b32 s15, s14, 3
	s_add_u32 s15, s15, s13
	s_lshl_b32 s14, s14, 6
	s_lshl_b32 s13, s13, 2
	s_add_u32 s14, s14, s13
	s_add_u32 s14, s14, 0x300
	s_add_u32 s12, s6, s14
	s_addc_u32 s13, s7, 0
	s_cmp_lg_u32 s80, 2
	s_cbranch_scc1 .Ltb_cached
	s_lshl_b32 s15, s15, 2
	s_add_u32 s15, s15, 0x200
	s_add_u32 s16, s6, s15
	s_addc_u32 s17, s7, 0
	v_readlane_b32 s20, v254, 40
	s_sub_u32 s20, s20, s6
	s_add_u32 s20, s20, 0x2000
	s_lshr_b32 s20, s20, 8
	s_lshl_b32 s20, s20, 2
	s_lshl_b32 s20, 4, s20
	global_load_dword v4, v129, s[16:17] sc1
	s_waitcnt vmcnt(0)
	v_readfirstlane_b32 s21, v4
	s_cmp_eq_u32 s21, s20
	s_cselect_b32 s21, 1, 0
	v_writelane_b32 v255, s21, 45
	s_branch .Ltb_haveflag

.Ltb_dep:
	global_load_dword v11, v5, s[6:7] sc1
	global_load_dword v12, v6, s[6:7] sc1
	global_load_dword v13, v7, s[6:7] sc1
	global_load_dword v14, v8, s[6:7] sc1
	global_load_dword v15, v9, s[6:7] sc1
	global_load_dword v16, v10, s[6:7] sc1
	s_waitcnt vmcnt(0)
	v_min3_u32 v11, v11, v12, v13
	v_min3_u32 v11, v11, v14, v15
	v_min_u32_e32 v11, v11, v16
	v_readfirstlane_b32 s20, v11
	s_cmp_ge_u32 s20, 20
	s_cbranch_scc1 .Ltb_nodep
	s_add_i32 s21, s21, 1
	s_cmp_lt_u32 s21, 0x2000
	s_cbranch_scc1 .Ltb_dep
